# recurrence waves: per-token sum-of-squares reduction via v_permlane16/32_swap instead of ds_bpermute
# speedup vs baseline: 1.0013x; 1.0013x over previous
; __device__ __forceinline__ void hgrn_unit(LAS unsigned char* lds, int b, int h, const bf16* Q, const bf16* KK, const bf16* V, const bf16* PBUF, const float* DBUF, bf16* Y, const float* onw) {
;     ...
;         v4u a0[4], a1[4];
; #pragma unroll
;         for (int kp = 0; kp < 4; ++kp) {
;             a0[kp] = (v4u){pk2(sacc0[2 * kp][0], sacc0[2 * kp][1]), pk2(sacc0[2 * kp][2], sacc0[2 * kp][3]), pk2(sacc0[2 * kp + 1][0], sacc0[2 * kp + 1][1]), pk2(sacc0[2 * kp + 1][2], sacc0[2 * kp + 1][3])};
;             a1[kp] = (v4u){pk2(sacc1[2 * kp][0], sacc1[2 * kp][1]), pk2(sacc1[2 * kp][2], sacc1[2 * kp][3]), pk2(sacc1[2 * kp + 1][0], sacc1[2 * kp + 1][1]), pk2(sacc1[2 * kp + 1][2], sacc1[2 * kp + 1][3])};
;         }
;         v4u av0[2], av1[2];
; #pragma unroll
;         for (int ks = 0; ks < 2; ++ks) { av0[ks] = tr_pair(vbase + 32 * ks * 136, 4 * 136); av1[ks] = tr_pair(vbase + 32 * ks * 136 + 16, 4 * 136); }
; #pragma unroll
;         for (int ti = 0; ti < 4; ++ti) {
;             v2u qf[8]; v4u pf[2];
; #pragma unroll
;             for (int kp = 0; kp < 4; ++kp) { qf[2 * kp] = *(const LAS v2u*)(qbase + 16 * ti * 136 + 32 * kp); qf[2 * kp + 1] = *(const LAS v2u*)(qbase + 16 * ti * 136 + 32 * kp + 16); }
;             pf[0] = *(const LAS v4u*)(pbase + 16 * ti * 72); pf[1] = *(const LAS v4u*)(pbase + 16 * ti * 72 + 32);
;             __builtin_amdgcn_sched_barrier(0);
;             f32x4 o0 = (f32x4){0.f, 0.f, 0.f, 0.f}, o1 = o0;
; #pragma unroll
;             for (int kp = 0; kp < 4; ++kp) {
;                 const bf16x8 bq = __builtin_bit_cast(bf16x8, ((v4u){qf[2 * kp].x, qf[2 * kp].y, qf[2 * kp + 1].x, qf[2 * kp + 1].y}));
;                 o0 = mfma16(__builtin_bit_cast(bf16x8, a0[kp]), bq, o0); o1 = mfma16(__builtin_bit_cast(bf16x8, a1[kp]), bq, o1);
;             }
;             o0 = mfma16(__builtin_bit_cast(bf16x8, av0[0]), __builtin_bit_cast(bf16x8, pf[0]), o0); o1 = mfma16(__builtin_bit_cast(bf16x8, av1[0]), __builtin_bit_cast(bf16x8, pf[0]), o1);
;             if (ti >= 2) { o0 = mfma16(__builtin_bit_cast(bf16x8, av0[1]), __builtin_bit_cast(bf16x8, pf[1]), o0); o1 = mfma16(__builtin_bit_cast(bf16x8, av1[1]), __builtin_bit_cast(bf16x8, pf[1]), o1); }
;             {
;                 float sa = (o0[0] * o0[0] + o0[1] * o0[1]) + (o0[2] * o0[2] + o0[3] * o0[3]), sb2 = (o1[0] * o1[0] + o1[1] * o1[1]) + (o1[2] * o1[2] + o1[3] * o1[3]);
.LBB0_1308:
	s_and_b32 s7, s2, 1
	s_mul_i32 s0, s7, 0xf200
	s_add_i32 s6, s0, 0
	v_lshl_add_u32 v135, v128, 1, s6
	v_lshlrev_b32_e32 v66, 1, v1
	v_add3_u32 v78, v135, s3, v66
	v_lshlrev_b32_e32 v79, 1, v126
	ds_read_b64_tr_b16 v[70:71], v78 offset:34848
	ds_read_b64_tr_b16 v[80:81], v78 offset:35904
	ds_read_b64_tr_b16 v[72:73], v78 offset:35936
	ds_read_b64_tr_b16 v[74:75], v78 offset:43520
	ds_read_b64_tr_b16 v[76:77], v78 offset:44608
	ds_read_b64_tr_b16 v[68:69], v78 offset:44640
	ds_read_b64_tr_b16 v[66:67], v78 offset:43552
	v_add3_u32 v162, s6, v130, v79
	v_lshlrev_b32_e32 v79, 1, v127
	v_add3_u32 v137, s6, v129, v79
	ds_read2_b64 v[114:117], v162 offset1:4
	ds_read2_b64 v[118:121], v162 offset0:8 offset1:12
	ds_read2_b64 v[122:125], v162 offset0:16 offset1:20
	ds_read2_b64 v[150:153], v162 offset0:24 offset1:28
	ds_read_b64_tr_b16 v[78:79], v78 offset:34816
	ds_read_b128 v[154:157], v137 offset:52224
	v_cvt_pk_bf16_f32 v82, v30, v31
	v_cvt_pk_bf16_f32 v83, v32, v33
	v_cvt_pk_bf16_f32 v84, v26, v27
	v_cvt_pk_bf16_f32 v85, v28, v29
	v_cvt_pk_bf16_f32 v86, v58, v59
	v_cvt_pk_bf16_f32 v87, v60, v61
	v_cvt_pk_bf16_f32 v88, v54, v55
	v_cvt_pk_bf16_f32 v89, v56, v57
	v_cvt_pk_bf16_f32 v90, v18, v19
	v_cvt_pk_bf16_f32 v91, v20, v21
	v_cvt_pk_bf16_f32 v92, v22, v23
	v_cvt_pk_bf16_f32 v93, v24, v25
	v_cvt_pk_bf16_f32 v94, v50, v51
	v_cvt_pk_bf16_f32 v95, v52, v53
	v_cvt_pk_bf16_f32 v96, v42, v43
	v_cvt_pk_bf16_f32 v97, v44, v45
	v_cvt_pk_bf16_f32 v98, v14, v15
	v_cvt_pk_bf16_f32 v99, v16, v17
	v_cvt_pk_bf16_f32 v100, v10, v11
	v_cvt_pk_bf16_f32 v101, v12, v13
	v_cvt_pk_bf16_f32 v102, v46, v47
	v_cvt_pk_bf16_f32 v103, v48, v49
	v_cvt_pk_bf16_f32 v104, v38, v39
	v_cvt_pk_bf16_f32 v105, v40, v41
	v_cvt_pk_bf16_f32 v106, v6, v7
	v_cvt_pk_bf16_f32 v107, v8, v9
	v_cvt_pk_bf16_f32 v108, v2, v3
	v_cvt_pk_bf16_f32 v109, v4, v5
	v_cvt_pk_bf16_f32 v110, v34, v35
	v_cvt_pk_bf16_f32 v111, v36, v37
	v_cvt_pk_bf16_f32 v112, v62, v63
	v_cvt_pk_bf16_f32 v113, v64, v65
	s_lshl_b32 s0, s7, 11
	s_waitcnt lgkmcnt(5)
	v_mfma_f32_16x16x32_bf16 v[164:167], v[82:85], v[114:117], 0
	v_add_u32_e32 v147, s0, v134
	v_mfma_f32_16x16x32_bf16 v[114:117], v[86:89], v[114:117], 0
	s_waitcnt lgkmcnt(4)
	v_mfma_f32_16x16x32_bf16 v[164:167], v[90:93], v[118:121], v[164:167]
	v_mfma_f32_16x16x32_bf16 v[114:117], v[94:97], v[118:121], v[114:117]
	s_waitcnt lgkmcnt(3)
	v_mfma_f32_16x16x32_bf16 v[118:121], v[98:101], v[122:125], v[164:167]
	v_mfma_f32_16x16x32_bf16 v[114:117], v[102:105], v[122:125], v[114:117]
	s_waitcnt lgkmcnt(2)
	v_mfma_f32_16x16x32_bf16 v[118:121], v[106:109], v[150:153], v[118:121]
	v_mfma_f32_16x16x32_bf16 v[114:117], v[110:113], v[150:153], v[114:117]
	s_waitcnt lgkmcnt(0)
	v_mfma_f32_16x16x32_bf16 v[118:121], v[78:81], v[154:157], v[118:121]
	v_mfma_f32_16x16x32_bf16 v[114:117], v[70:73], v[154:157], v[114:117]
	s_nop 6
	v_mov_b32_e32 v124, v119
	v_mov_b32_e32 v125, v115
	v_mov_b32_e32 v122, v118
	v_mov_b32_e32 v123, v114
	v_pk_mul_f32 v[124:125], v[124:125], v[124:125]
	v_mov_b32_e32 v150, v121
	v_mov_b32_e32 v151, v117
	v_pk_fma_f32 v[122:123], v[122:123], v[122:123], v[124:125]
	v_mov_b32_e32 v124, v120
	v_mov_b32_e32 v125, v116
	v_pk_mul_f32 v[150:151], v[150:151], v[150:151]
	s_nop 0
	v_pk_fma_f32 v[124:125], v[124:125], v[124:125], v[150:151]
	s_nop 0
	v_pk_add_f32 v[122:123], v[122:123], v[124:125]
	v_mov_b32_e32 v124, v122
	v_mov_b32_e32 v125, v123
	s_nop 1
	v_permlane16_swap_b32_e32 v124, v122
	v_permlane16_swap_b32_e32 v125, v123
	s_waitcnt lgkmcnt(0)
	v_pk_add_f32 v[122:123], v[122:123], v[124:125]
	v_mov_b32_e32 v124, v122
	v_mov_b32_e32 v125, v123
	s_nop 1
	v_permlane32_swap_b32_e32 v124, v122
	v_permlane32_swap_b32_e32 v125, v123
	s_and_saveexec_b64 s[0:1], vcc
	s_cbranch_execz .LBB0_1310
	s_waitcnt lgkmcnt(0)
	v_pk_add_f32 v[122:123], v[122:123], v[124:125]
	ds_write_b64 v147, v[122:123]
.LBB0_1310:
	s_or_b64 exec, exec, s[0:1]
	s_mulk_i32 s7, 0x4400
	v_cvt_pk_bf16_f32 v118, v118, v119
	v_cvt_pk_bf16_f32 v119, v120, v121
	v_add_u32_e32 v136, s7, v131
	v_cvt_pk_bf16_f32 v114, v114, v115
	v_cvt_pk_bf16_f32 v115, v116, v117
	ds_write2_b64 v136, v[118:119], v[114:115] offset1:4
	v_add_u32_e32 v150, 0x1000, v162
	ds_read2_b64 v[114:117], v150 offset0:32 offset1:36
	ds_read2_b64 v[118:121], v150 offset0:40 offset1:44
	s_waitcnt lgkmcnt(3)
	ds_read2_b64 v[122:125], v150 offset0:48 offset1:52
	ds_read2_b64 v[150:153], v150 offset0:56 offset1:60
	ds_read_b128 v[154:157], v137 offset:54528
	s_waitcnt lgkmcnt(4)
	v_mfma_f32_16x16x32_bf16 v[164:167], v[82:85], v[114:117], 0
	v_mfma_f32_16x16x32_bf16 v[114:117], v[86:89], v[114:117], 0
	s_waitcnt lgkmcnt(3)
	v_mfma_f32_16x16x32_bf16 v[164:167], v[90:93], v[118:121], v[164:167]
	v_mfma_f32_16x16x32_bf16 v[114:117], v[94:97], v[118:121], v[114:117]
	s_waitcnt lgkmcnt(2)
	v_mfma_f32_16x16x32_bf16 v[118:121], v[98:101], v[122:125], v[164:167]
	v_mfma_f32_16x16x32_bf16 v[114:117], v[102:105], v[122:125], v[114:117]
	s_waitcnt lgkmcnt(1)
	v_mfma_f32_16x16x32_bf16 v[118:121], v[106:109], v[150:153], v[118:121]
	v_mfma_f32_16x16x32_bf16 v[122:125], v[110:113], v[150:153], v[114:117]
	s_waitcnt lgkmcnt(0)
	v_mfma_f32_16x16x32_bf16 v[114:117], v[78:81], v[154:157], v[118:121]
	v_mfma_f32_16x16x32_bf16 v[118:121], v[70:73], v[154:157], v[122:125]
	s_nop 6
	v_mov_b32_e32 v122, v115
	v_mov_b32_e32 v123, v119
	v_mov_b32_e32 v150, v114
	v_mov_b32_e32 v151, v118
	v_pk_mul_f32 v[122:123], v[122:123], v[122:123]
	v_mov_b32_e32 v124, v116
	v_pk_fma_f32 v[122:123], v[150:151], v[150:151], v[122:123]
	v_mov_b32_e32 v150, v117
	v_mov_b32_e32 v151, v121
	v_mov_b32_e32 v125, v120
	v_pk_mul_f32 v[150:151], v[150:151], v[150:151]
	s_nop 0
	v_pk_fma_f32 v[124:125], v[124:125], v[124:125], v[150:151]
	s_nop 0
	v_pk_add_f32 v[122:123], v[122:123], v[124:125]
	v_mov_b32_e32 v124, v122
	v_mov_b32_e32 v125, v123
	s_nop 1
	v_permlane16_swap_b32_e32 v124, v122
	v_permlane16_swap_b32_e32 v125, v123
	s_waitcnt lgkmcnt(0)
	v_pk_add_f32 v[122:123], v[122:123], v[124:125]
	v_mov_b32_e32 v124, v122
	v_mov_b32_e32 v125, v123
	s_nop 1
	v_permlane32_swap_b32_e32 v124, v122
	v_permlane32_swap_b32_e32 v125, v123
	s_and_saveexec_b64 s[0:1], vcc
	s_cbranch_execz .LBB0_1312
	s_waitcnt lgkmcnt(0)
	v_pk_add_f32 v[122:123], v[122:123], v[124:125]
	ds_write_b64 v147, v[122:123] offset:512
; #define LAS __attribute__((address_space(3)))
; __device__ __forceinline__ unsigned pk2(float lo, float hi) { f32x2_t v = {lo, hi}; bf16x2_t b = __builtin_convertvector(v, bf16x2_t); return __builtin_bit_cast(unsigned, b); }
; __device__ __forceinline__ void hgrn_unit(LAS unsigned char* lds, int b, int h, const bf16* Q, const bf16* KK, const bf16* V, const bf16* PBUF, const float* DBUF, bf16* Y, const float* onw) {
;     ...
; #pragma unroll
;         for (int ti = 0; ti < 4; ++ti) {
;             v2u qf[8]; v4u pf[2];
; #pragma unroll
;             for (int kp = 0; kp < 4; ++kp) { qf[2 * kp] = *(const LAS v2u*)(qbase + 16 * ti * 136 + 32 * kp); qf[2 * kp + 1] = *(const LAS v2u*)(qbase + 16 * ti * 136 + 32 * kp + 16); }
;             pf[0] = *(const LAS v4u*)(pbase + 16 * ti * 72); pf[1] = *(const LAS v4u*)(pbase + 16 * ti * 72 + 32);
;             __builtin_amdgcn_sched_barrier(0);
;             f32x4 o0 = (f32x4){0.f, 0.f, 0.f, 0.f}, o1 = o0;
; #pragma unroll
;             for (int kp = 0; kp < 4; ++kp) {
;                 const bf16x8 bq = __builtin_bit_cast(bf16x8, ((v4u){qf[2 * kp].x, qf[2 * kp].y, qf[2 * kp + 1].x, qf[2 * kp + 1].y}));
;                 o0 = mfma16(__builtin_bit_cast(bf16x8, a0[kp]), bq, o0); o1 = mfma16(__builtin_bit_cast(bf16x8, a1[kp]), bq, o1);
;             }
;             o0 = mfma16(__builtin_bit_cast(bf16x8, av0[0]), __builtin_bit_cast(bf16x8, pf[0]), o0); o1 = mfma16(__builtin_bit_cast(bf16x8, av1[0]), __builtin_bit_cast(bf16x8, pf[0]), o1);
;             if (ti >= 2) { o0 = mfma16(__builtin_bit_cast(bf16x8, av0[1]), __builtin_bit_cast(bf16x8, pf[1]), o0); o1 = mfma16(__builtin_bit_cast(bf16x8, av1[1]), __builtin_bit_cast(bf16x8, pf[1]), o1); }
;             {
;                 float sa = (o0[0] * o0[0] + o0[1] * o0[1]) + (o0[2] * o0[2] + o0[3] * o0[3]), sb2 = (o1[0] * o1[0] + o1[1] * o1[1]) + (o1[2] * o1[2] + o1[3] * o1[3]);
;                 sa += __shfl_xor(sa, 16); sa += __shfl_xor(sa, 32); sb2 += __shfl_xor(sb2, 16); sb2 += __shfl_xor(sb2, 32);
;                 if (g4 == 0) { sqw[(16 * ti + l16) * 8 + wt] = sa; sqw[(16 * ti + l16) * 8 + wt + 1] = sb2; }
;                 *(LAS v2u*)(obw + 16 * ti * 136) = (v2u){pk2(o0[0], o0[1]), pk2(o0[2], o0[3])}; *(LAS v2u*)(obw + 16 * ti * 136 + 16) = (v2u){pk2(o1[0], o1[1]), pk2(o1[2], o1[3])};
;             }
.LBB0_1312:
	s_or_b64 exec, exec, s[0:1]
	v_cvt_pk_bf16_f32 v114, v114, v115
	v_cvt_pk_bf16_f32 v115, v116, v117
	v_cvt_pk_bf16_f32 v116, v118, v119
	v_cvt_pk_bf16_f32 v117, v120, v121
	v_add_u32_e32 v118, 0x1000, v136
	ds_write2_b64 v118, v[114:115], v[116:117] offset0:32 offset1:36
	v_add_u32_e32 v150, 0x2000, v162
	ds_read2_b64 v[114:117], v150 offset0:64 offset1:68
	ds_read2_b64 v[118:121], v150 offset0:72 offset1:76
	s_waitcnt lgkmcnt(3)
	ds_read2_b64 v[122:125], v150 offset0:80 offset1:84
	ds_read2_b64 v[150:153], v150 offset0:88 offset1:92
	ds_read_b128 v[154:157], v137 offset:56832
	ds_read_b128 v[164:167], v137 offset:56896
	s_waitcnt lgkmcnt(5)
	v_mfma_f32_16x16x32_bf16 v[168:171], v[82:85], v[114:117], 0
	v_mfma_f32_16x16x32_bf16 v[114:117], v[86:89], v[114:117], 0
	s_waitcnt lgkmcnt(4)
	v_mfma_f32_16x16x32_bf16 v[168:171], v[90:93], v[118:121], v[168:171]
	v_mfma_f32_16x16x32_bf16 v[114:117], v[94:97], v[118:121], v[114:117]
	s_waitcnt lgkmcnt(3)
	v_mfma_f32_16x16x32_bf16 v[118:121], v[98:101], v[122:125], v[168:171]
	v_mfma_f32_16x16x32_bf16 v[114:117], v[102:105], v[122:125], v[114:117]
	s_waitcnt lgkmcnt(2)
	v_mfma_f32_16x16x32_bf16 v[118:121], v[106:109], v[150:153], v[118:121]
	v_mfma_f32_16x16x32_bf16 v[114:117], v[110:113], v[150:153], v[114:117]
	s_waitcnt lgkmcnt(1)
	v_mfma_f32_16x16x32_bf16 v[118:121], v[78:81], v[154:157], v[118:121]
	v_mfma_f32_16x16x32_bf16 v[122:125], v[70:73], v[154:157], v[114:117]
	s_waitcnt lgkmcnt(0)
	v_mfma_f32_16x16x32_bf16 v[114:117], v[74:77], v[164:167], v[118:121]
	v_mfma_f32_16x16x32_bf16 v[118:121], v[66:69], v[164:167], v[122:125]
	s_nop 6
	v_mov_b32_e32 v122, v115
	v_mov_b32_e32 v123, v119
	v_mov_b32_e32 v150, v114
	v_mov_b32_e32 v151, v118
	v_pk_mul_f32 v[122:123], v[122:123], v[122:123]
	v_mov_b32_e32 v124, v116
	v_pk_fma_f32 v[122:123], v[150:151], v[150:151], v[122:123]
	v_mov_b32_e32 v150, v117
	v_mov_b32_e32 v151, v121
	v_mov_b32_e32 v125, v120
	v_pk_mul_f32 v[150:151], v[150:151], v[150:151]
	s_nop 0
	v_pk_fma_f32 v[124:125], v[124:125], v[124:125], v[150:151]
	s_nop 0
	v_pk_add_f32 v[122:123], v[122:123], v[124:125]
	v_mov_b32_e32 v124, v122
	v_mov_b32_e32 v125, v123
	s_nop 1
	v_permlane16_swap_b32_e32 v124, v122
	v_permlane16_swap_b32_e32 v125, v123
	s_waitcnt lgkmcnt(0)
	v_pk_add_f32 v[122:123], v[122:123], v[124:125]
	v_mov_b32_e32 v124, v122
	v_mov_b32_e32 v125, v123
	s_nop 1
	v_permlane32_swap_b32_e32 v124, v122
	v_permlane32_swap_b32_e32 v125, v123
	s_and_saveexec_b64 s[0:1], vcc
	s_cbranch_execz .LBB0_1314
	s_waitcnt lgkmcnt(0)
	v_pk_add_f32 v[122:123], v[122:123], v[124:125]
	ds_write_b64 v147, v[122:123] offset:1024
.LBB0_1314:
	s_or_b64 exec, exec, s[0:1]
	v_cvt_pk_bf16_f32 v114, v114, v115
	v_cvt_pk_bf16_f32 v115, v116, v117
	v_cvt_pk_bf16_f32 v116, v118, v119
	v_cvt_pk_bf16_f32 v117, v120, v121
	v_add_u32_e32 v118, 0x2000, v136
	ds_write2_b64 v118, v[114:115], v[116:117] offset0:64 offset1:68
	v_add_u32_e32 v150, 0x3000, v162
	ds_read2_b64 v[114:117], v150 offset0:96 offset1:100
	ds_read2_b64 v[118:121], v150 offset0:104 offset1:108
	s_waitcnt lgkmcnt(3)
	ds_read2_b64 v[122:125], v150 offset0:112 offset1:116
	ds_read2_b64 v[150:153], v150 offset0:120 offset1:124
	ds_read_b128 v[154:157], v137 offset:59136
	ds_read_b128 v[162:165], v137 offset:59200
	s_waitcnt lgkmcnt(5)
	v_mfma_f32_16x16x32_bf16 v[82:85], v[82:85], v[114:117], 0
	v_mfma_f32_16x16x32_bf16 v[86:89], v[86:89], v[114:117], 0
	s_waitcnt lgkmcnt(4)
	v_mfma_f32_16x16x32_bf16 v[82:85], v[90:93], v[118:121], v[82:85]
	v_mfma_f32_16x16x32_bf16 v[86:89], v[94:97], v[118:121], v[86:89]
	s_waitcnt lgkmcnt(3)
	v_mfma_f32_16x16x32_bf16 v[82:85], v[98:101], v[122:125], v[82:85]
	v_mfma_f32_16x16x32_bf16 v[86:89], v[102:105], v[122:125], v[86:89]
	s_waitcnt lgkmcnt(2)
	v_mfma_f32_16x16x32_bf16 v[82:85], v[106:109], v[150:153], v[82:85]
	v_mfma_f32_16x16x32_bf16 v[86:89], v[110:113], v[150:153], v[86:89]
	s_waitcnt lgkmcnt(1)
	v_mfma_f32_16x16x32_bf16 v[82:85], v[78:81], v[154:157], v[82:85]
	v_mfma_f32_16x16x32_bf16 v[86:89], v[70:73], v[154:157], v[86:89]
	s_waitcnt lgkmcnt(0)
	v_mfma_f32_16x16x32_bf16 v[82:85], v[74:77], v[162:165], v[82:85]
	v_mfma_f32_16x16x32_bf16 v[86:89], v[66:69], v[162:165], v[86:89]
	s_nop 6
	v_mov_b32_e32 v92, v83
	v_mov_b32_e32 v93, v87
	v_mov_b32_e32 v90, v82
	v_mov_b32_e32 v91, v86
	v_pk_mul_f32 v[92:93], v[92:93], v[92:93]
	v_mov_b32_e32 v94, v85
	v_mov_b32_e32 v95, v89
	v_pk_fma_f32 v[90:91], v[90:91], v[90:91], v[92:93]
	v_mov_b32_e32 v92, v84
	v_mov_b32_e32 v93, v88
	v_pk_mul_f32 v[94:95], v[94:95], v[94:95]
	s_nop 0
	v_pk_fma_f32 v[92:93], v[92:93], v[92:93], v[94:95]
	s_nop 0
	v_pk_add_f32 v[90:91], v[90:91], v[92:93]
	v_mov_b32_e32 v92, v90
	v_mov_b32_e32 v93, v91
	s_nop 1
	v_permlane16_swap_b32_e32 v92, v90
	v_permlane16_swap_b32_e32 v93, v91
	s_waitcnt lgkmcnt(0)
	v_pk_add_f32 v[90:91], v[90:91], v[92:93]
	v_mov_b32_e32 v92, v90
	v_mov_b32_e32 v93, v91
	s_nop 1
	v_permlane32_swap_b32_e32 v92, v90
	v_permlane32_swap_b32_e32 v93, v91
	s_and_saveexec_b64 s[0:1], vcc
	s_cbranch_execz .LBB0_1307
	s_waitcnt lgkmcnt(0)
	v_pk_add_f32 v[90:91], v[90:91], v[92:93]
	ds_write_b64 v147, v[90:91] offset:1536
	s_branch .LBB0_1307
